# P6 K-loop: LDS-DMA loads addressed as scalar base + precomputed 32-bit lane offsets (17 vector 64-bit adds per iteration removed)
# baseline (speedup 1.0000x reference)
.LBB0_1370:
	s_add_u32 s53, s56, 0x100
	s_addc_u32 s72, s57, 0
	s_ashr_i32 s51, s50, 31
	s_lshl_b64 s[26:27], s[50:51], 21
	s_add_u32 s54, s30, s26
	s_addc_u32 s55, s31, s27
	s_and_b64 s[26:27], s[6:7], exec
	s_cselect_b32 s51, s55, s19
	s_cselect_b32 s73, s54, s18
	s_ashr_i32 s49, s48, 31
	s_lshl_b64 s[26:27], s[48:49], 21
	v_readlane_b32 s58, v254, 9
	v_readlane_b32 s59, v254, 10
	s_add_u32 s26, s58, s26
	s_addc_u32 s27, s59, s27
	s_and_b64 s[58:59], s[6:7], exec
	s_cselect_b32 s49, s27, s57
	s_cselect_b32 s76, s26, s56
	v_lshl_add_u64 v[140:141], s[18:19], 0, v[134:135]
	s_mov_b32 s77, -2
	s_mov_b64 s[56:57], 0
	v_add_u32_e32 v222, s64, v143
	v_add_u32_e32 v223, s64, v144
	v_add_u32_e32 v224, s65, v143
	v_add_u32_e32 v225, s65, v144
	v_add_u32_e32 v226, s66, v143
	v_add_u32_e32 v227, s66, v144
	v_add_u32_e32 v228, s67, v143
	v_add_u32_e32 v229, s67, v144
	v_add_u32_e32 v230, s70, v143
	v_add_u32_e32 v231, s70, v144
	v_add_u32_e32 v232, s68, v143
	v_add_u32_e32 v233, s68, v144
	v_add_u32_e32 v234, s71, v143
	v_add_u32_e32 v235, s71, v144
	v_add_u32_e32 v236, s69, v143
	v_add_u32_e32 v237, s69, v144
	v_add_u32_e32 v238, s24, v134
	v_add_u32_e32 v239, s44, v134
	v_add_u32_e32 v240, s28, v134
	v_add_u32_e32 v241, s46, v134
	v_add_u32_e32 v242, s10, v132
	v_add_u32_e32 v243, s14, v132
	v_add_u32_e32 v244, s16, v132
	v_add_u32_e32 v245, s20, v0
	v_add_u32_e32 v246, s10, v0
	v_add_u32_e32 v247, s22, v0
	v_add_u32_e32 v248, s24, v132
	v_add_u32_e32 v249, s28, v132
	v_add_u32_e32 v250, s36, v132
	v_add_u32_e32 v251, s40, v132
.LBB0_1371:
	ds_read_b128 v[148:151], v222
	ds_read_b128 v[152:155], v223
	s_add_u32 s58, s18, s56
	ds_read_b128 v[158:161], v224
	ds_read_b128 v[162:165], v225
	s_addc_u32 s59, s19, s57
	ds_read_b128 v[170:173], v226
	ds_read_b128 v[174:177], v227
	s_add_u32 s58, s58, 0x100
	ds_read_b128 v[178:181], v228
	ds_read_b128 v[182:185], v229
	s_addc_u32 s59, s59, 0
	s_add_u32 s78, s53, s56
	s_addc_u32 s79, s72, s57
	s_cmpk_eq_i32 s56, 0x1f00
	s_cselect_b32 s79, s49, s79
	s_cselect_b32 s78, s76, s78
	s_cselect_b32 s59, s51, s59
	s_cselect_b32 s58, s73, s58
	s_add_u32 s98, s18, s56
	s_addc_u32 s99, s19, s57
	s_add_i32 m0, s35, 0x8000
	ds_read_b128 v[186:189], v145
	ds_read_b128 v[190:193], v145 offset:2048
	ds_read_b128 v[194:197], v146
	ds_read_b128 v[198:201], v146 offset:2048
	ds_read_b128 v[202:205], v145 offset:4096
	ds_read_b128 v[206:209], v145 offset:6144
	ds_read_b128 v[210:213], v146 offset:4096
	ds_read_b128 v[214:217], v146 offset:6144
	global_load_lds_dwordx4 v238, s[98:99]
	s_add_i32 m0, s35, 0xa000
	s_nop 0
	global_load_lds_dwordx4 v239, s[98:99]
	s_add_i32 m0, s35, 0xc000
	s_nop 0
	global_load_lds_dwordx4 v240, s[98:99]
	s_add_i32 m0, s35, 0xe000
	s_nop 0
	global_load_lds_dwordx4 v241, s[98:99]
	s_waitcnt vmcnt(8)
	s_waitcnt lgkmcnt(0)
	s_barrier
	v_mfma_f32_16x16x32_bf16 v[128:131], v[148:151], v[186:189], v[128:131]
	v_mfma_f32_16x16x32_bf16 v[128:131], v[152:155], v[194:197], v[128:131]
	v_mfma_f32_16x16x32_bf16 v[112:115], v[152:155], v[198:201], v[112:115]
	v_mfma_f32_16x16x32_bf16 v[112:115], v[148:151], v[190:193], v[112:115]
	v_mfma_f32_16x16x32_bf16 v[96:99], v[148:151], v[202:205], v[96:99]
	v_mfma_f32_16x16x32_bf16 v[96:99], v[152:155], v[210:213], v[96:99]
	v_mfma_f32_16x16x32_bf16 v[80:83], v[152:155], v[214:217], v[80:83]
	v_mfma_f32_16x16x32_bf16 v[80:83], v[148:151], v[206:209], v[80:83]
	v_mfma_f32_16x16x32_bf16 v[76:79], v[158:161], v[206:209], v[76:79]
	v_mfma_f32_16x16x32_bf16 v[76:79], v[162:165], v[214:217], v[76:79]
	v_mfma_f32_16x16x32_bf16 v[92:95], v[162:165], v[210:213], v[92:95]
	v_mfma_f32_16x16x32_bf16 v[92:95], v[158:161], v[202:205], v[92:95]
	v_mfma_f32_16x16x32_bf16 v[108:111], v[158:161], v[190:193], v[108:111]
	v_mfma_f32_16x16x32_bf16 v[108:111], v[162:165], v[198:201], v[108:111]
	v_mfma_f32_16x16x32_bf16 v[124:127], v[162:165], v[194:197], v[124:127]
	v_mfma_f32_16x16x32_bf16 v[124:127], v[158:161], v[186:189], v[124:127]
	v_mfma_f32_16x16x32_bf16 v[120:123], v[170:173], v[186:189], v[120:123]
	v_mfma_f32_16x16x32_bf16 v[120:123], v[174:177], v[194:197], v[120:123]
	v_mfma_f32_16x16x32_bf16 v[104:107], v[174:177], v[198:201], v[104:107]
	v_mfma_f32_16x16x32_bf16 v[104:107], v[170:173], v[190:193], v[104:107]
	v_mfma_f32_16x16x32_bf16 v[88:91], v[170:173], v[202:205], v[88:91]
	v_mfma_f32_16x16x32_bf16 v[88:91], v[174:177], v[210:213], v[88:91]
	v_mfma_f32_16x16x32_bf16 v[72:75], v[174:177], v[214:217], v[72:75]
	v_mfma_f32_16x16x32_bf16 v[72:75], v[170:173], v[206:209], v[72:75]
	v_mfma_f32_16x16x32_bf16 v[68:71], v[178:181], v[206:209], v[68:71]
	v_mfma_f32_16x16x32_bf16 v[68:71], v[182:185], v[214:217], v[68:71]
	v_mfma_f32_16x16x32_bf16 v[84:87], v[182:185], v[210:213], v[84:87]
	v_mfma_f32_16x16x32_bf16 v[84:87], v[178:181], v[202:205], v[84:87]
	v_mfma_f32_16x16x32_bf16 v[100:103], v[178:181], v[190:193], v[100:103]
	v_mfma_f32_16x16x32_bf16 v[100:103], v[182:185], v[198:201], v[100:103]
	v_mfma_f32_16x16x32_bf16 v[116:119], v[182:185], v[194:197], v[116:119]
	v_mfma_f32_16x16x32_bf16 v[116:119], v[178:181], v[186:189], v[116:119]
	s_barrier
	s_mov_b64 s[100:101], s[78:79]
	s_add_i32 s78, s64, s34
	s_mov_b32 m0, s78
	ds_read_b128 v[186:189], v145 offset:16384
	ds_read_b128 v[190:193], v145 offset:18432
	ds_read_b128 v[194:197], v146 offset:16384
	ds_read_b128 v[198:201], v146 offset:18432
	ds_read_b128 v[202:205], v145 offset:20480
	ds_read_b128 v[206:209], v145 offset:22528
	ds_read_b128 v[210:213], v146 offset:20480
	ds_read_b128 v[214:217], v146 offset:22528
	global_load_lds_dwordx4 v132, s[100:101]
	s_add_i32 m0, s78, 0x2000
	s_add_i32 s78, s66, s34
	global_load_lds_dwordx4 v242, s[100:101]
	s_mov_b32 m0, s78
	s_nop 0
	global_load_lds_dwordx4 v243, s[100:101]
	s_add_i32 m0, s78, 0x2000
	s_nop 0
	global_load_lds_dwordx4 v244, s[100:101]
	s_waitcnt vmcnt(4)
	s_waitcnt lgkmcnt(0)
	s_barrier
	v_mfma_f32_16x16x32_bf16 v[64:67], v[148:151], v[186:189], v[64:67]
	v_mfma_f32_16x16x32_bf16 v[64:67], v[152:155], v[194:197], v[64:67]
	v_mfma_f32_16x16x32_bf16 v[48:51], v[152:155], v[198:201], v[48:51]
	v_mfma_f32_16x16x32_bf16 v[48:51], v[148:151], v[190:193], v[48:51]
	v_mfma_f32_16x16x32_bf16 v[32:35], v[148:151], v[202:205], v[32:35]
	v_mfma_f32_16x16x32_bf16 v[32:35], v[152:155], v[210:213], v[32:35]
	v_mfma_f32_16x16x32_bf16 v[16:19], v[152:155], v[214:217], v[16:19]
	v_mfma_f32_16x16x32_bf16 v[16:19], v[148:151], v[206:209], v[16:19]
	v_mfma_f32_16x16x32_bf16 v[12:15], v[158:161], v[206:209], v[12:15]
	v_mfma_f32_16x16x32_bf16 v[12:15], v[162:165], v[214:217], v[12:15]
	v_mfma_f32_16x16x32_bf16 v[28:31], v[162:165], v[210:213], v[28:31]
	v_mfma_f32_16x16x32_bf16 v[28:31], v[158:161], v[202:205], v[28:31]
	v_mfma_f32_16x16x32_bf16 v[44:47], v[158:161], v[190:193], v[44:47]
	v_mfma_f32_16x16x32_bf16 v[44:47], v[162:165], v[198:201], v[44:47]
	v_mfma_f32_16x16x32_bf16 v[60:63], v[162:165], v[194:197], v[60:63]
	v_mfma_f32_16x16x32_bf16 v[60:63], v[158:161], v[186:189], v[60:63]
	v_mfma_f32_16x16x32_bf16 v[56:59], v[170:173], v[186:189], v[56:59]
	v_mfma_f32_16x16x32_bf16 v[56:59], v[174:177], v[194:197], v[56:59]
	v_mfma_f32_16x16x32_bf16 v[40:43], v[174:177], v[198:201], v[40:43]
	v_mfma_f32_16x16x32_bf16 v[40:43], v[170:173], v[190:193], v[40:43]
	v_mfma_f32_16x16x32_bf16 v[24:27], v[170:173], v[202:205], v[24:27]
	v_mfma_f32_16x16x32_bf16 v[24:27], v[174:177], v[210:213], v[24:27]
	v_mfma_f32_16x16x32_bf16 v[8:11], v[174:177], v[214:217], v[8:11]
	v_mfma_f32_16x16x32_bf16 v[8:11], v[170:173], v[206:209], v[8:11]
	v_mfma_f32_16x16x32_bf16 v[4:7], v[178:181], v[206:209], v[4:7]
	v_mfma_f32_16x16x32_bf16 v[4:7], v[182:185], v[214:217], v[4:7]
	v_mfma_f32_16x16x32_bf16 v[20:23], v[182:185], v[210:213], v[20:23]
	v_mfma_f32_16x16x32_bf16 v[20:23], v[178:181], v[202:205], v[20:23]
	v_mfma_f32_16x16x32_bf16 v[36:39], v[178:181], v[190:193], v[36:39]
	v_mfma_f32_16x16x32_bf16 v[36:39], v[182:185], v[198:201], v[36:39]
	v_mfma_f32_16x16x32_bf16 v[52:55], v[182:185], v[194:197], v[52:55]
	v_mfma_f32_16x16x32_bf16 v[52:55], v[178:181], v[186:189], v[52:55]
	s_barrier
	ds_read_b128 v[148:151], v230
	ds_read_b128 v[152:155], v231
	ds_read_b128 v[158:161], v232
	ds_read_b128 v[162:165], v233
	ds_read_b128 v[170:173], v234
	ds_read_b128 v[174:177], v235
	ds_read_b128 v[178:181], v236
	ds_read_b128 v[182:185], v237
	s_mov_b32 m0, s35
	ds_read_b128 v[186:189], v145 offset:32768
	ds_read_b128 v[190:193], v145 offset:34816
	ds_read_b128 v[194:197], v146 offset:32768
	ds_read_b128 v[198:201], v146 offset:34816
	ds_read_b128 v[202:205], v145 offset:36864
	ds_read_b128 v[206:209], v145 offset:38912
	ds_read_b128 v[210:213], v146 offset:36864
	ds_read_b128 v[214:217], v146 offset:38912
	global_load_lds_dwordx4 v0, s[58:59]
	s_mov_b32 m0, s39
	s_nop 0
	global_load_lds_dwordx4 v245, s[58:59]
	s_mov_b32 m0, s60
	s_nop 0
	global_load_lds_dwordx4 v246, s[58:59]
	s_mov_b32 m0, s61
	s_nop 0
	global_load_lds_dwordx4 v247, s[58:59]
	s_waitcnt vmcnt(8)
	s_waitcnt lgkmcnt(0)
	s_barrier
	v_mfma_f32_16x16x32_bf16 v[128:131], v[148:151], v[186:189], v[128:131]
	v_mfma_f32_16x16x32_bf16 v[128:131], v[152:155], v[194:197], v[128:131]
	v_mfma_f32_16x16x32_bf16 v[112:115], v[152:155], v[198:201], v[112:115]
	v_mfma_f32_16x16x32_bf16 v[112:115], v[148:151], v[190:193], v[112:115]
	v_mfma_f32_16x16x32_bf16 v[96:99], v[148:151], v[202:205], v[96:99]
	v_mfma_f32_16x16x32_bf16 v[96:99], v[152:155], v[210:213], v[96:99]
	v_mfma_f32_16x16x32_bf16 v[80:83], v[152:155], v[214:217], v[80:83]
	v_mfma_f32_16x16x32_bf16 v[80:83], v[148:151], v[206:209], v[80:83]
	v_mfma_f32_16x16x32_bf16 v[76:79], v[158:161], v[206:209], v[76:79]
	v_mfma_f32_16x16x32_bf16 v[76:79], v[162:165], v[214:217], v[76:79]
	v_mfma_f32_16x16x32_bf16 v[92:95], v[162:165], v[210:213], v[92:95]
	v_mfma_f32_16x16x32_bf16 v[92:95], v[158:161], v[202:205], v[92:95]
	v_mfma_f32_16x16x32_bf16 v[108:111], v[158:161], v[190:193], v[108:111]
	v_mfma_f32_16x16x32_bf16 v[108:111], v[162:165], v[198:201], v[108:111]
	v_mfma_f32_16x16x32_bf16 v[124:127], v[162:165], v[194:197], v[124:127]
	v_mfma_f32_16x16x32_bf16 v[124:127], v[158:161], v[186:189], v[124:127]
	v_mfma_f32_16x16x32_bf16 v[120:123], v[170:173], v[186:189], v[120:123]
	v_mfma_f32_16x16x32_bf16 v[120:123], v[174:177], v[194:197], v[120:123]
	v_mfma_f32_16x16x32_bf16 v[104:107], v[174:177], v[198:201], v[104:107]
	v_mfma_f32_16x16x32_bf16 v[104:107], v[170:173], v[190:193], v[104:107]
	v_mfma_f32_16x16x32_bf16 v[88:91], v[170:173], v[202:205], v[88:91]
	v_mfma_f32_16x16x32_bf16 v[88:91], v[174:177], v[210:213], v[88:91]
	v_mfma_f32_16x16x32_bf16 v[72:75], v[174:177], v[214:217], v[72:75]
	v_mfma_f32_16x16x32_bf16 v[72:75], v[170:173], v[206:209], v[72:75]
	v_mfma_f32_16x16x32_bf16 v[68:71], v[178:181], v[206:209], v[68:71]
	v_mfma_f32_16x16x32_bf16 v[68:71], v[182:185], v[214:217], v[68:71]
	v_mfma_f32_16x16x32_bf16 v[84:87], v[182:185], v[210:213], v[84:87]
	v_mfma_f32_16x16x32_bf16 v[84:87], v[178:181], v[202:205], v[84:87]
	v_mfma_f32_16x16x32_bf16 v[100:103], v[178:181], v[190:193], v[100:103]
	v_mfma_f32_16x16x32_bf16 v[100:103], v[182:185], v[198:201], v[100:103]
	v_mfma_f32_16x16x32_bf16 v[116:119], v[182:185], v[194:197], v[116:119]
	v_mfma_f32_16x16x32_bf16 v[116:119], v[178:181], v[186:189], v[116:119]
	s_barrier
	s_add_i32 s58, s70, s34
	s_mov_b32 m0, s58
	ds_read_b128 v[186:189], v145 offset:49152
	ds_read_b128 v[190:193], v145 offset:51200
	ds_read_b128 v[194:197], v146 offset:49152
	ds_read_b128 v[198:201], v146 offset:51200
	ds_read_b128 v[202:205], v145 offset:53248
	ds_read_b128 v[206:209], v145 offset:55296
	ds_read_b128 v[210:213], v146 offset:53248
	ds_read_b128 v[214:217], v146 offset:55296
	global_load_lds_dwordx4 v248, s[100:101]
	s_add_i32 m0, s58, 0x2000
	s_add_i32 s58, s71, s34
	global_load_lds_dwordx4 v249, s[100:101]
	s_mov_b32 m0, s58
	s_nop 0
	global_load_lds_dwordx4 v250, s[100:101]
	s_add_i32 m0, s58, 0x2000
	s_nop 0
	global_load_lds_dwordx4 v251, s[100:101]
	s_waitcnt vmcnt(4)
	s_waitcnt lgkmcnt(0)
	s_barrier
	v_mfma_f32_16x16x32_bf16 v[64:67], v[148:151], v[186:189], v[64:67]
	v_mfma_f32_16x16x32_bf16 v[64:67], v[152:155], v[194:197], v[64:67]
	v_mfma_f32_16x16x32_bf16 v[48:51], v[152:155], v[198:201], v[48:51]
	v_mfma_f32_16x16x32_bf16 v[48:51], v[148:151], v[190:193], v[48:51]
	v_mfma_f32_16x16x32_bf16 v[32:35], v[148:151], v[202:205], v[32:35]
	v_mfma_f32_16x16x32_bf16 v[32:35], v[152:155], v[210:213], v[32:35]
	v_mfma_f32_16x16x32_bf16 v[16:19], v[152:155], v[214:217], v[16:19]
	v_mfma_f32_16x16x32_bf16 v[16:19], v[148:151], v[206:209], v[16:19]
	v_mfma_f32_16x16x32_bf16 v[12:15], v[158:161], v[206:209], v[12:15]
	v_mfma_f32_16x16x32_bf16 v[12:15], v[162:165], v[214:217], v[12:15]
	v_mfma_f32_16x16x32_bf16 v[28:31], v[162:165], v[210:213], v[28:31]
	v_mfma_f32_16x16x32_bf16 v[28:31], v[158:161], v[202:205], v[28:31]
	v_mfma_f32_16x16x32_bf16 v[44:47], v[158:161], v[190:193], v[44:47]
	v_mfma_f32_16x16x32_bf16 v[44:47], v[162:165], v[198:201], v[44:47]
	v_mfma_f32_16x16x32_bf16 v[60:63], v[162:165], v[194:197], v[60:63]
	v_mfma_f32_16x16x32_bf16 v[60:63], v[158:161], v[186:189], v[60:63]
	v_mfma_f32_16x16x32_bf16 v[56:59], v[170:173], v[186:189], v[56:59]
	v_mfma_f32_16x16x32_bf16 v[56:59], v[174:177], v[194:197], v[56:59]
	v_mfma_f32_16x16x32_bf16 v[40:43], v[174:177], v[198:201], v[40:43]
	v_mfma_f32_16x16x32_bf16 v[40:43], v[170:173], v[190:193], v[40:43]
	v_mfma_f32_16x16x32_bf16 v[24:27], v[170:173], v[202:205], v[24:27]
	v_mfma_f32_16x16x32_bf16 v[24:27], v[174:177], v[210:213], v[24:27]
	v_mfma_f32_16x16x32_bf16 v[8:11], v[174:177], v[214:217], v[8:11]
	v_mfma_f32_16x16x32_bf16 v[8:11], v[170:173], v[206:209], v[8:11]
	v_mfma_f32_16x16x32_bf16 v[4:7], v[178:181], v[206:209], v[4:7]
	v_mfma_f32_16x16x32_bf16 v[4:7], v[182:185], v[214:217], v[4:7]
	v_mfma_f32_16x16x32_bf16 v[20:23], v[182:185], v[210:213], v[20:23]
	v_mfma_f32_16x16x32_bf16 v[20:23], v[178:181], v[202:205], v[20:23]
	v_mfma_f32_16x16x32_bf16 v[36:39], v[178:181], v[190:193], v[36:39]
	v_mfma_f32_16x16x32_bf16 v[36:39], v[182:185], v[198:201], v[36:39]
	v_mfma_f32_16x16x32_bf16 v[52:55], v[182:185], v[194:197], v[52:55]
	v_mfma_f32_16x16x32_bf16 v[52:55], v[178:181], v[186:189], v[52:55]
	s_barrier
	s_add_i32 s77, s77, 2
	s_add_u32 s56, s56, 0x100
	s_addc_u32 s57, s57, 0
	s_cmp_gt_u32 s77, 61
	s_cbranch_scc0 .LBB0_1371
	s_add_u32 s56, s53, 0xffffff00
	s_addc_u32 s57, s72, -1
	s_andn2_b64 vcc, exec, s[6:7]
	s_cbranch_vccnz .LBB0_1362
	v_mov_b32_e32 v4, 0
	s_mov_b32 s0, s48
	s_mov_b32 s8, s50
	s_mov_b64 s[18:19], s[54:55]
	s_mov_b32 s63, s52
	v_mov_b32_e32 v5, v4
	v_mov_b32_e32 v6, v4
	v_mov_b32_e32 v7, v4
	v_mov_b32_e32 v8, v4
	v_mov_b32_e32 v9, v4
	v_mov_b32_e32 v10, v4
	v_mov_b32_e32 v11, v4
	v_mov_b32_e32 v20, v4
	v_mov_b32_e32 v21, v4
	v_mov_b32_e32 v22, v4
	v_mov_b32_e32 v23, v4
	v_mov_b32_e32 v24, v4
	v_mov_b32_e32 v25, v4
	v_mov_b32_e32 v26, v4
	v_mov_b32_e32 v27, v4
	v_mov_b32_e32 v36, v4
	v_mov_b32_e32 v37, v4
	v_mov_b32_e32 v38, v4
	v_mov_b32_e32 v39, v4
	v_mov_b32_e32 v40, v4
	v_mov_b32_e32 v41, v4
	v_mov_b32_e32 v42, v4
	v_mov_b32_e32 v43, v4
	v_mov_b32_e32 v52, v4
	v_mov_b32_e32 v53, v4
	v_mov_b32_e32 v54, v4
	v_mov_b32_e32 v55, v4
	v_mov_b32_e32 v56, v4
	v_mov_b32_e32 v57, v4
	v_mov_b32_e32 v58, v4
	v_mov_b32_e32 v59, v4
	v_mov_b32_e32 v12, v4
	v_mov_b32_e32 v13, v4
	v_mov_b32_e32 v14, v4
	v_mov_b32_e32 v15, v4
	v_mov_b32_e32 v16, v4
	v_mov_b32_e32 v17, v4
	v_mov_b32_e32 v18, v4
	v_mov_b32_e32 v19, v4
	v_mov_b32_e32 v28, v4
	v_mov_b32_e32 v29, v4
	v_mov_b32_e32 v30, v4
	v_mov_b32_e32 v31, v4
	v_mov_b32_e32 v32, v4
	v_mov_b32_e32 v33, v4
	v_mov_b32_e32 v34, v4
	v_mov_b32_e32 v35, v4
	v_mov_b32_e32 v44, v4
	v_mov_b32_e32 v45, v4
	v_mov_b32_e32 v46, v4
	v_mov_b32_e32 v47, v4
	v_mov_b32_e32 v48, v4
	v_mov_b32_e32 v49, v4
	v_mov_b32_e32 v50, v4
	v_mov_b32_e32 v51, v4
	v_mov_b32_e32 v60, v4
	v_mov_b32_e32 v61, v4
	v_mov_b32_e32 v62, v4
	v_mov_b32_e32 v63, v4
	v_mov_b32_e32 v64, v4
	v_mov_b32_e32 v65, v4
	v_mov_b32_e32 v66, v4
	v_mov_b32_e32 v67, v4
	v_mov_b32_e32 v68, v4
	v_mov_b32_e32 v69, v4
	v_mov_b32_e32 v70, v4
	v_mov_b32_e32 v71, v4
	v_mov_b32_e32 v72, v4
	v_mov_b32_e32 v73, v4
	v_mov_b32_e32 v74, v4
	v_mov_b32_e32 v75, v4
	v_mov_b32_e32 v84, v4
	v_mov_b32_e32 v85, v4
	v_mov_b32_e32 v86, v4
	v_mov_b32_e32 v87, v4
	v_mov_b32_e32 v88, v4
	v_mov_b32_e32 v89, v4
	v_mov_b32_e32 v90, v4
	v_mov_b32_e32 v91, v4
	v_mov_b32_e32 v100, v4
	v_mov_b32_e32 v101, v4
	v_mov_b32_e32 v102, v4
	v_mov_b32_e32 v103, v4
	v_mov_b32_e32 v104, v4
	v_mov_b32_e32 v105, v4
	v_mov_b32_e32 v106, v4
	v_mov_b32_e32 v107, v4
	v_mov_b32_e32 v116, v4
	v_mov_b32_e32 v117, v4
	v_mov_b32_e32 v118, v4
	v_mov_b32_e32 v119, v4
	v_mov_b32_e32 v120, v4
	v_mov_b32_e32 v121, v4
	v_mov_b32_e32 v122, v4
	v_mov_b32_e32 v123, v4
	v_mov_b32_e32 v76, v4
	v_mov_b32_e32 v77, v4
	v_mov_b32_e32 v78, v4
	v_mov_b32_e32 v79, v4
	v_mov_b32_e32 v80, v4
	v_mov_b32_e32 v81, v4
	v_mov_b32_e32 v82, v4
	v_mov_b32_e32 v83, v4
	v_mov_b32_e32 v92, v4
	v_mov_b32_e32 v93, v4
	v_mov_b32_e32 v94, v4
	v_mov_b32_e32 v95, v4
	v_mov_b32_e32 v96, v4
	v_mov_b32_e32 v97, v4
	v_mov_b32_e32 v98, v4
	v_mov_b32_e32 v99, v4
	v_mov_b32_e32 v108, v4
	v_mov_b32_e32 v109, v4
	v_mov_b32_e32 v110, v4
	v_mov_b32_e32 v111, v4
	v_mov_b32_e32 v112, v4
	v_mov_b32_e32 v113, v4
	v_mov_b32_e32 v114, v4
	v_mov_b32_e32 v115, v4
	v_mov_b32_e32 v124, v4
	v_mov_b32_e32 v125, v4
	v_mov_b32_e32 v126, v4
	v_mov_b32_e32 v127, v4
	v_mov_b32_e32 v128, v4
	v_mov_b32_e32 v129, v4
	v_mov_b32_e32 v130, v4
	v_mov_b32_e32 v131, v4
	s_andn2_b64 vcc, exec, s[4:5]
	s_cbranch_vccnz .LBB0_1363
